# GLA scan: next-chunk q/k/low-rank prefetch issued at the top of section D instead of before the barrier that publishes qe/ke
# baseline (speedup 1.0000x reference)
; __device__ __forceinline__ int v_st(int k, int c) { const int kk = (k & ~0xC) | ((k & 4) << 1) | ((k & 8) >> 1); return ((kk >> 3) * 4 + (c >> 5)) * 512 + ((kk & 7) * 32 + (c & 31)) * 2; }
; __device__ __forceinline__ float bf2f(short s) { return __uint_as_float(((unsigned)(unsigned short)s) << 16); }
; __device__ __forceinline__ float bf2f(u16 u) { return __uint_as_float((unsigned)u << 16); }
; __device__ __forceinline__ u16 f2bf(float f) { return (u16)(pk2(f, 0.f) & 0xffffu); }
; __device__ __forceinline__ void scan_unit(const int unit, const Args& a, unsigned char* lds, const int mk_wid) {
;     ...
;           u16* qcol = qe + (g * 16) * QP + c; u16* kcol = ke + (g * 16) * QP + c; unsigned char* kdb = lds + L_KD + v_st(g * 16, c);
; #pragma unroll
;           for (int ii = 0; ii < 16; ++ii) { const float bb = bl[ii] + off;
;               const float qf = bf2f(qcol[ii * QP]), kf = bf2f(kcol[ii * QP]);
;               const float e = __builtin_amdgcn_exp2f(bb * 1.4426950408889634f), ker = kf * __builtin_amdgcn_rcpf(e);
;               qcol[ii * QP] = f2bf(qf * (0.088388347648318440f * e));
;               kcol[ii * QP] = f2bf(ker);
;               *(u16*)(kdb + v_st(ii, 0)) = f2bf(ker * dlc); } }
;         if (step + 1 < 36) GLA_LOAD(step + 1);
.Lscan_c2_nodl:
	v_mov_b32_e32 v71, 0xffff0000
	v_lshlrev_b32_e32 v218, 16, v128
	v_and_b32_e32 v219, v71, v128
	v_lshlrev_b32_e32 v220, 16, v100
	v_and_b32_e32 v221, v71, v100
	v_pk_mul_f32 v[218:219], v[170:171], v[218:219]
	v_pk_mul_f32 v[220:221], v[186:187], v[220:221]
	v_cvt_pk_bf16_f32 v224, v218, v219
	v_pk_mul_f32 v[222:223], v[92:93], v[220:221]
	v_cvt_pk_bf16_f32 v225, v220, v221
	ds_write_b32 v254, v224
	ds_write_b32 v254, v225 offset:17408
	v_cvt_pk_bf16_f32 v226, v222, v223
	ds_write_b32 v255, v226 offset:34816
	v_lshlrev_b32_e32 v228, 16, v129
	v_and_b32_e32 v229, v71, v129
	v_lshlrev_b32_e32 v230, 16, v101
	v_and_b32_e32 v231, v71, v101
	v_pk_mul_f32 v[228:229], v[172:173], v[228:229]
	v_pk_mul_f32 v[230:231], v[188:189], v[230:231]
	v_cvt_pk_bf16_f32 v234, v228, v229
	v_pk_mul_f32 v[232:233], v[92:93], v[230:231]
	v_cvt_pk_bf16_f32 v235, v230, v231
	ds_write_b32 v254, v234 offset:272
	ds_write_b32 v254, v235 offset:17680
	v_cvt_pk_bf16_f32 v236, v232, v233
	ds_write_b32 v255, v236 offset:34880
	v_lshlrev_b32_e32 v218, 16, v130
	v_and_b32_e32 v219, v71, v130
	v_lshlrev_b32_e32 v220, 16, v102
	v_and_b32_e32 v221, v71, v102
	v_pk_mul_f32 v[218:219], v[174:175], v[218:219]
	v_pk_mul_f32 v[220:221], v[190:191], v[220:221]
	v_cvt_pk_bf16_f32 v224, v218, v219
	v_pk_mul_f32 v[222:223], v[92:93], v[220:221]
	v_cvt_pk_bf16_f32 v225, v220, v221
	ds_write_b32 v254, v224 offset:544
	ds_write_b32 v254, v225 offset:17952
	v_cvt_pk_bf16_f32 v226, v222, v223
	ds_write_b32 v255, v226 offset:34944
	v_lshlrev_b32_e32 v228, 16, v131
	v_and_b32_e32 v229, v71, v131
	v_lshlrev_b32_e32 v230, 16, v103
	v_and_b32_e32 v231, v71, v103
	v_pk_mul_f32 v[228:229], v[176:177], v[228:229]
	v_pk_mul_f32 v[230:231], v[192:193], v[230:231]
	v_cvt_pk_bf16_f32 v234, v228, v229
	v_pk_mul_f32 v[232:233], v[92:93], v[230:231]
	v_cvt_pk_bf16_f32 v235, v230, v231
	ds_write_b32 v254, v234 offset:816
	ds_write_b32 v254, v235 offset:18224
	v_cvt_pk_bf16_f32 v236, v232, v233
	ds_write_b32 v255, v236 offset:35008
	v_lshlrev_b32_e32 v218, 16, v132
	v_and_b32_e32 v219, v71, v132
	v_lshlrev_b32_e32 v220, 16, v104
	v_and_b32_e32 v221, v71, v104
	v_pk_mul_f32 v[218:219], v[178:179], v[218:219]
	v_pk_mul_f32 v[220:221], v[194:195], v[220:221]
	v_cvt_pk_bf16_f32 v224, v218, v219
	v_pk_mul_f32 v[222:223], v[92:93], v[220:221]
	v_cvt_pk_bf16_f32 v225, v220, v221
	ds_write_b32 v254, v224 offset:1088
	ds_write_b32 v254, v225 offset:18496
	v_cvt_pk_bf16_f32 v226, v222, v223
	ds_write_b32 v255, v226 offset:36864
	v_lshlrev_b32_e32 v228, 16, v133
	v_and_b32_e32 v229, v71, v133
	v_lshlrev_b32_e32 v230, 16, v105
	v_and_b32_e32 v231, v71, v105
	v_pk_mul_f32 v[228:229], v[180:181], v[228:229]
	v_pk_mul_f32 v[230:231], v[196:197], v[230:231]
	v_cvt_pk_bf16_f32 v234, v228, v229
	v_pk_mul_f32 v[232:233], v[92:93], v[230:231]
	v_cvt_pk_bf16_f32 v235, v230, v231
	ds_write_b32 v254, v234 offset:1360
	ds_write_b32 v254, v235 offset:18768
	v_cvt_pk_bf16_f32 v236, v232, v233
	ds_write_b32 v255, v236 offset:36928
	v_lshlrev_b32_e32 v218, 16, v134
	v_and_b32_e32 v219, v71, v134
	v_lshlrev_b32_e32 v220, 16, v106
	v_and_b32_e32 v221, v71, v106
	v_pk_mul_f32 v[218:219], v[182:183], v[218:219]
	v_pk_mul_f32 v[220:221], v[198:199], v[220:221]
	v_cvt_pk_bf16_f32 v224, v218, v219
	v_pk_mul_f32 v[222:223], v[92:93], v[220:221]
	v_cvt_pk_bf16_f32 v225, v220, v221
	ds_write_b32 v254, v224 offset:1632
	ds_write_b32 v254, v225 offset:19040
	v_cvt_pk_bf16_f32 v226, v222, v223
	ds_write_b32 v255, v226 offset:36992
	v_lshlrev_b32_e32 v228, 16, v135
	v_and_b32_e32 v229, v71, v135
	v_lshlrev_b32_e32 v230, 16, v107
	v_and_b32_e32 v231, v71, v107
	v_pk_mul_f32 v[228:229], v[184:185], v[228:229]
	v_pk_mul_f32 v[230:231], v[200:201], v[230:231]
	v_cvt_pk_bf16_f32 v234, v228, v229
	v_pk_mul_f32 v[232:233], v[92:93], v[230:231]
	v_cvt_pk_bf16_f32 v235, v230, v231
	ds_write_b32 v254, v234 offset:1904
	ds_write_b32 v254, v235 offset:19312
	v_cvt_pk_bf16_f32 v236, v232, v233
	ds_write_b32 v255, v236 offset:37056
	s_waitcnt vmcnt(0)
	s_add_i32 s58, s5, 1
	s_mov_b32 s99, -1
	s_cmp_eq_u32 s50, 3
	s_cbranch_scc1 .LBB0_435
	v_mbcnt_lo_u32_b32 v64, -1, 0
	v_mbcnt_hi_u32_b32 v64, -1, v64
	s_andn2_b64 vcc, exec, s[6:7]
	v_add_u32_e32 v70, s72, v64
	s_mov_b32 s34, s58
	s_cbranch_vccnz .LBB0_426
	s_cmp_gt_u32 s5, 2
	s_mov_b32 s34, s50
	s_cbranch_scc1 .LBB0_426
	s_sub_i32 s34, 2, s5
.LBB0_426:
	s_mov_b32 s99, s34

; __device__ __forceinline__ void scan_unit(const int unit, const Args& a, unsigned char* lds, const int mk_wid) {
;     ...
;         if (step + 1 < 36) GLA_LOAD(step + 1);
.LBB0_438:
.LBB0_439:
	s_cmp_lt_i32 s99, 0
	s_cbranch_scc1 .Lscan_pfmv_skip
	s_lshl_b32 s96, s99, 16
	s_lshl_b32 s97, s99, 12
	v_add_u32_e32 v64, s96, v245
	v_add_u32_e32 v65, 0x1000, v64
	s_cmp_lt_i32 s99, 4
	s_cbranch_scc1 .Lscan_pf_noq
	s_bitcmp1_b32 s8, 0
	s_cbranch_scc1 .Lscan_qk_rev0
	global_load_dword v100, v64, s[14:15]
	global_load_dword v128, v64, s[22:23]
	global_load_dword v101, v64, s[14:15] offset:1024
	global_load_dword v129, v64, s[22:23] offset:1024
	global_load_dword v102, v64, s[14:15] offset:2048
	global_load_dword v130, v64, s[22:23] offset:2048
	global_load_dword v103, v64, s[14:15] offset:3072
	global_load_dword v131, v64, s[22:23] offset:3072
	global_load_dword v104, v65, s[14:15]
	global_load_dword v132, v65, s[22:23]
	global_load_dword v105, v65, s[14:15] offset:1024
	global_load_dword v133, v65, s[22:23] offset:1024
	global_load_dword v106, v65, s[14:15] offset:2048
	global_load_dword v134, v65, s[22:23] offset:2048
	global_load_dword v107, v65, s[14:15] offset:3072
	global_load_dword v135, v65, s[22:23] offset:3072
	s_branch .Lscan_qk_done0

.Lscan_pf_v:
	v_add_u32_e32 v70, s97, v251
	v_mov_b32_e32 v71, 0
	v_lshl_add_u64 v[70:71], v[152:153], 0, v[70:71]
	global_load_dwordx4 v[96:99], v[70:71], off
